# SwiGLU epilogue: 64 v_pk_mul_f32 split into scalar v_mul_f32 pairs (packed f32 issues slower than two singles)
# speedup vs baseline: 1.0049x; 1.0011x over previous
; DI unsigned pk2(float lo, float hi) { f32x2 v = {lo, hi}; bf16v2 b = __builtin_convertvector(v, bf16v2); return __builtin_bit_cast(unsigned, b); }
; DI float silu_f(float x) { return x * __builtin_amdgcn_rcpf(1.f + __expf(-x)); }
;     DI void operator()(const f32x4 (&acc)[2][2][4][2], const Unit& u, int wr, int wc, int fr, int fq) const {
;         const int row0 = u.pm * BM + wr * 64 + fr, col0 = u.pn * HALF + wc * 32 + 8 * fq;
; #pragma unroll
;         for (int ai = 0; ai < 2; ++ai)
; #pragma unroll
;             for (int m = 0; m < 4; ++m) { bf16_t* rowp = O + (size_t)(row0 + ai * HALF + m * 16) * ldc + col0;
;                 float r[8];
; #pragma unroll
;                 for (int n = 0; n < 2; ++n)
; #pragma unroll
;                     for (int e = 0; e < 4; ++e) { const float g = acc[ai][0][m][n][e], up = acc[ai][1][m][n][e]; r[n * 4 + e] = silu_f(g) * up; }
;                 u32x4 o; o.x = pk2(r[0], r[1]); o.y = pk2(r[2], r[3]); o.z = pk2(r[4], r[5]); o.w = pk2(r[6], r[7]);
;                 *(u32x4*)rowp = o; }
.Lgemm_epi:
	v_lshl_add_u32 v140, s80, 8, v145
	v_ashrrev_i32_e32 v138, 31, v140
	v_mul_lo_u32 v157, s78, v138
	v_mul_lo_u32 v141, s79, v140
	v_mad_u64_u32 v[138:139], s[18:19], s78, v140, 0
	v_or_b32_e32 v162, 16, v140
	v_or_b32_e32 v160, 32, v140
	v_or_b32_e32 v158, 48, v140
	v_add_u32_e32 v154, 0x80, v140
	v_add_u32_e32 v151, 0x90, v140
	v_add3_u32 v139, v139, v157, v141
	s_mov_b64 s[18:19], -1
	s_andn2_b64 vcc, exec, s[14:15]
	v_mul_lo_u32 v163, s79, v162
	v_mul_lo_u32 v161, s79, v160
	v_mul_lo_u32 v159, s79, v158
	v_ashrrev_i32_e32 v156, 31, v154
	v_mul_lo_u32 v155, s79, v154
	v_ashrrev_i32_e32 v153, 31, v151
	v_mul_lo_u32 v152, s79, v151
	v_add_u32_e32 v150, 0xa0, v140
	v_add_u32_e32 v149, 0xb0, v140
	s_cbranch_vccnz .LBB0_746
	s_lshl_b32 s100, s78, 5
	s_mov_b32 s101, 0
	v_mul_f32_e32 v140, 0xbfb8aa3b, v24
	v_mul_f32_e32 v141, 0xbfb8aa3b, v25
	v_mul_f32_e32 v166, 0xbfb8aa3b, v26
	v_mul_f32_e32 v167, 0xbfb8aa3b, v27
	v_mul_f32_e32 v168, 0xbfb8aa3b, v28
	v_mul_f32_e32 v169, 0xbfb8aa3b, v29
	v_exp_f32_e32 v140, v140
	v_exp_f32_e32 v141, v141
	v_exp_f32_e32 v166, v166
	v_exp_f32_e32 v167, v167
	v_exp_f32_e32 v168, v168
	v_exp_f32_e32 v169, v169
	v_mul_f32_e32 v170, 0xbfb8aa3b, v30
	v_mul_f32_e32 v171, 0xbfb8aa3b, v31
	v_add_f32_e32 v140, 1.0, v140
	v_add_f32_e32 v141, 1.0, v141
	v_add_f32_e32 v166, 1.0, v166
	v_add_f32_e32 v167, 1.0, v167
	v_add_f32_e32 v168, 1.0, v168
	v_add_f32_e32 v169, 1.0, v169
	v_exp_f32_e32 v170, v170
	v_exp_f32_e32 v171, v171
	v_rcp_f32_e32 v164, v140
	v_rcp_f32_e32 v165, v141
	v_rcp_f32_e32 v166, v166
	v_rcp_f32_e32 v167, v167
	v_rcp_f32_e32 v168, v168
	v_rcp_f32_e32 v169, v169
	v_add_f32_e32 v170, 1.0, v170
	v_add_f32_e32 v171, 1.0, v171
	v_mul_f32_e32 v164, v24, v164
	v_mul_f32_e32 v165, v25, v165
	v_mul_f32_e32 v166, v26, v166
	v_mul_f32_e32 v167, v27, v167
	v_rcp_f32_e32 v170, v170
	v_rcp_f32_e32 v171, v171
	v_mul_f32_e32 v168, v28, v168
	v_mul_f32_e32 v169, v29, v169
	v_mul_f32_e32 v164, v164, v88
	v_mul_f32_e32 v165, v165, v89
	v_mul_f32_e32 v166, v166, v90
	v_mul_f32_e32 v167, v167, v91
	v_mul_f32_e32 v168, v168, v96
	v_mul_f32_e32 v169, v169, v97
	v_cvt_pk_bf16_f32 v164, v164, v165
	v_cvt_pk_bf16_f32 v165, v166, v167
	v_cvt_pk_bf16_f32 v166, v168, v169
	v_mul_f32_e32 v168, 0xbfb8aa3b, v16
	v_mul_f32_e32 v169, 0xbfb8aa3b, v17
	v_lshl_or_b32 v140, s77, 7, v147
	v_readlane_b32 s18, v255, 30
	v_exp_f32_e32 v168, v168
	v_exp_f32_e32 v169, v169
	v_ashrrev_i32_e32 v141, 31, v140
	v_readlane_b32 s19, v255, 31
	v_mul_f32_e32 v170, v30, v170
	v_mul_f32_e32 v171, v31, v171
	s_nop 0
	v_lshl_add_u64 v[140:141], v[140:141], 1, s[18:19]
	v_mul_f32_e32 v170, v170, v98
	v_mul_f32_e32 v171, v171, v99
	v_lshl_add_u64 v[174:175], v[138:139], 1, v[140:141]
	v_cvt_pk_bf16_f32 v167, v170, v171
	global_store_dwordx4 v[174:175], v[164:167], off
	s_nop 1
	v_mul_f32_e32 v170, 0xbfb8aa3b, v20
	v_mul_f32_e32 v171, 0xbfb8aa3b, v21
	v_add_f32_e32 v164, 1.0, v168
	v_add_f32_e32 v165, 1.0, v169
	v_mul_f32_e32 v168, 0xbfb8aa3b, v18
	v_mul_f32_e32 v169, 0xbfb8aa3b, v19
	v_exp_f32_e32 v168, v168
	v_exp_f32_e32 v169, v169
	v_mul_f32_e32 v172, 0xbfb8aa3b, v22
	v_mul_f32_e32 v173, 0xbfb8aa3b, v23
	v_add_f32_e32 v168, 1.0, v168
	v_add_f32_e32 v169, 1.0, v169
	v_exp_f32_e32 v170, v170
	v_exp_f32_e32 v171, v171
	v_exp_f32_e32 v172, v172
	v_exp_f32_e32 v173, v173
	v_rcp_f32_e32 v164, v164
	v_rcp_f32_e32 v165, v165
	v_rcp_f32_e32 v168, v168
	v_rcp_f32_e32 v169, v169
	v_add_f32_e32 v170, 1.0, v170
	v_add_f32_e32 v171, 1.0, v171
	v_add_f32_e32 v172, 1.0, v172
	v_add_f32_e32 v173, 1.0, v173
	v_mul_f32_e32 v164, v16, v164
	v_mul_f32_e32 v165, v17, v165
	v_mul_f32_e32 v168, v18, v168
	v_mul_f32_e32 v169, v19, v169
	v_rcp_f32_e32 v170, v170
	v_rcp_f32_e32 v171, v171
	v_rcp_f32_e32 v172, v172
	v_rcp_f32_e32 v173, v173
	v_mul_f32_e32 v164, v164, v80
	v_mul_f32_e32 v165, v165, v81
	v_mul_f32_e32 v168, v168, v82
	v_mul_f32_e32 v169, v169, v83
	v_cvt_pk_bf16_f32 v164, v164, v165
	v_cvt_pk_bf16_f32 v165, v168, v169
	v_mul_f32_e32 v168, 0xbfb8aa3b, v8
	v_mul_f32_e32 v169, 0xbfb8aa3b, v9
	v_exp_f32_e32 v168, v168
	v_exp_f32_e32 v169, v169
	v_mul_f32_e32 v170, v20, v170
	v_mul_f32_e32 v171, v21, v171
	v_mul_f32_e32 v172, v22, v172
	v_mul_f32_e32 v173, v23, v173
	v_mul_f32_e32 v170, v170, v84
	v_mul_f32_e32 v171, v171, v85
	v_mul_f32_e32 v172, v172, v86
	v_mul_f32_e32 v173, v173, v87
	v_lshl_add_u64 v[174:175], v[174:175], 0, s[100:101]
	v_cvt_pk_bf16_f32 v166, v170, v171
	v_cvt_pk_bf16_f32 v167, v172, v173
	global_store_dwordx4 v[174:175], v[164:167], off
	s_nop 1
	v_mul_f32_e32 v170, 0xbfb8aa3b, v12
	v_mul_f32_e32 v171, 0xbfb8aa3b, v13
	v_add_f32_e32 v164, 1.0, v168
	v_add_f32_e32 v165, 1.0, v169
	v_mul_f32_e32 v168, 0xbfb8aa3b, v10
	v_mul_f32_e32 v169, 0xbfb8aa3b, v11
	v_exp_f32_e32 v168, v168
	v_exp_f32_e32 v169, v169
	v_mul_f32_e32 v172, 0xbfb8aa3b, v14
	v_mul_f32_e32 v173, 0xbfb8aa3b, v15
	v_add_f32_e32 v168, 1.0, v168
	v_add_f32_e32 v169, 1.0, v169
	v_exp_f32_e32 v170, v170
	v_exp_f32_e32 v171, v171
	v_exp_f32_e32 v172, v172
	v_exp_f32_e32 v173, v173
	v_rcp_f32_e32 v164, v164
	v_rcp_f32_e32 v165, v165
	v_rcp_f32_e32 v168, v168
	v_rcp_f32_e32 v169, v169
	v_add_f32_e32 v170, 1.0, v170
	v_add_f32_e32 v171, 1.0, v171
	v_add_f32_e32 v172, 1.0, v172
	v_add_f32_e32 v173, 1.0, v173
	v_mul_f32_e32 v164, v8, v164
	v_mul_f32_e32 v165, v9, v165
	v_mul_f32_e32 v168, v10, v168
	v_mul_f32_e32 v169, v11, v169
	v_rcp_f32_e32 v170, v170
	v_rcp_f32_e32 v171, v171
	v_rcp_f32_e32 v172, v172
	v_rcp_f32_e32 v173, v173
	v_mul_f32_e32 v164, v164, v72
	v_mul_f32_e32 v165, v165, v73
	v_mul_f32_e32 v168, v168, v74
	v_mul_f32_e32 v169, v169, v75
	v_cvt_pk_bf16_f32 v164, v164, v165
; DI unsigned pk2(float lo, float hi) { f32x2 v = {lo, hi}; bf16v2 b = __builtin_convertvector(v, bf16v2); return __builtin_bit_cast(unsigned, b); }
; DI float silu_f(float x) { return x * __builtin_amdgcn_rcpf(1.f + __expf(-x)); }
;     DI void operator()(const f32x4 (&acc)[2][2][4][2], const Unit& u, int wr, int wc, int fr, int fq) const {
;     ...
;             for (int m = 0; m < 4; ++m) { bf16_t* rowp = O + (size_t)(row0 + ai * HALF + m * 16) * ldc + col0;
;                 float r[8];
; #pragma unroll
;                 for (int n = 0; n < 2; ++n)
; #pragma unroll
;                     for (int e = 0; e < 4; ++e) { const float g = acc[ai][0][m][n][e], up = acc[ai][1][m][n][e]; r[n * 4 + e] = silu_f(g) * up; }
;                 u32x4 o; o.x = pk2(r[0], r[1]); o.y = pk2(r[2], r[3]); o.z = pk2(r[4], r[5]); o.w = pk2(r[6], r[7]);
;                 *(u32x4*)rowp = o; }
	v_cvt_pk_bf16_f32 v165, v168, v169
	v_mul_f32_e32 v168, 0xbfb8aa3b, v0
	v_mul_f32_e32 v169, 0xbfb8aa3b, v1
	v_exp_f32_e32 v168, v168
	v_exp_f32_e32 v169, v169
	v_mul_f32_e32 v170, v12, v170
	v_mul_f32_e32 v171, v13, v171
	v_mul_f32_e32 v172, v14, v172
	v_mul_f32_e32 v173, v15, v173
	v_mul_f32_e32 v170, v170, v76
	v_mul_f32_e32 v171, v171, v77
	v_mul_f32_e32 v172, v172, v78
	v_mul_f32_e32 v173, v173, v79
	v_lshl_add_u64 v[174:175], v[174:175], 0, s[100:101]
	v_cvt_pk_bf16_f32 v166, v170, v171
	v_cvt_pk_bf16_f32 v167, v172, v173
	global_store_dwordx4 v[174:175], v[164:167], off
	s_nop 1
	v_mul_f32_e32 v170, 0xbfb8aa3b, v4
	v_mul_f32_e32 v171, 0xbfb8aa3b, v5
	v_add_f32_e32 v164, 1.0, v168
	v_add_f32_e32 v165, 1.0, v169
	v_mul_f32_e32 v168, 0xbfb8aa3b, v2
	v_mul_f32_e32 v169, 0xbfb8aa3b, v3
	v_mul_f32_e32 v172, 0xbfb8aa3b, v6
	v_mul_f32_e32 v173, 0xbfb8aa3b, v7
	v_exp_f32_e32 v168, v168
	v_exp_f32_e32 v169, v169
	v_exp_f32_e32 v170, v170
	v_exp_f32_e32 v171, v171
	v_exp_f32_e32 v172, v172
	v_exp_f32_e32 v173, v173
	v_add_f32_e32 v168, 1.0, v168
	v_add_f32_e32 v169, 1.0, v169
	v_add_f32_e32 v170, 1.0, v170
	v_add_f32_e32 v171, 1.0, v171
	v_add_f32_e32 v172, 1.0, v172
	v_add_f32_e32 v173, 1.0, v173
	v_rcp_f32_e32 v164, v164
	v_rcp_f32_e32 v165, v165
	v_rcp_f32_e32 v168, v168
	v_rcp_f32_e32 v169, v169
	v_rcp_f32_e32 v170, v170
	v_rcp_f32_e32 v171, v171
	v_rcp_f32_e32 v172, v172
	v_rcp_f32_e32 v173, v173
	v_mul_f32_e32 v164, v0, v164
	v_mul_f32_e32 v165, v1, v165
	v_mul_f32_e32 v168, v2, v168
	v_mul_f32_e32 v169, v3, v169
	v_mul_f32_e32 v170, v4, v170
	v_mul_f32_e32 v171, v5, v171
	v_mul_f32_e32 v172, v6, v172
	v_mul_f32_e32 v173, v7, v173
	v_mul_f32_e32 v164, v164, v56
	v_mul_f32_e32 v165, v165, v57
	v_mul_f32_e32 v168, v168, v58
	v_mul_f32_e32 v169, v169, v59
	v_mul_f32_e32 v170, v170, v64
	v_mul_f32_e32 v171, v171, v65
	v_mul_f32_e32 v172, v172, v66
	v_mul_f32_e32 v173, v173, v67
	v_lshl_add_u64 v[174:175], v[174:175], 0, s[100:101]
	v_cvt_pk_bf16_f32 v164, v164, v165
	v_cvt_pk_bf16_f32 v165, v168, v169
	v_cvt_pk_bf16_f32 v166, v170, v171
	v_cvt_pk_bf16_f32 v167, v172, v173
	global_store_dwordx4 v[174:175], v[164:167], off
	s_nop 1
	v_mul_f32_e32 v169, 0xbfb8aa3b, v63
	v_mul_f32_e32 v164, 0xbfb8aa3b, v60
	v_mul_f32_e32 v165, 0xbfb8aa3b, v61
	v_mul_f32_e32 v168, 0xbfb8aa3b, v62
	v_mul_f32_e32 v170, 0xbfb8aa3b, v68
	v_mul_f32_e32 v171, 0xbfb8aa3b, v69
	v_mul_f32_e32 v172, 0xbfb8aa3b, v70
	v_mul_f32_e32 v173, 0xbfb8aa3b, v71
	v_exp_f32_e32 v164, v164
	v_exp_f32_e32 v165, v165
	v_exp_f32_e32 v168, v168
	v_exp_f32_e32 v169, v169
	v_exp_f32_e32 v170, v170
	v_exp_f32_e32 v171, v171
	v_exp_f32_e32 v172, v172
	v_exp_f32_e32 v173, v173
	v_add_f32_e32 v164, 1.0, v164
	v_add_f32_e32 v165, 1.0, v165
	v_add_f32_e32 v168, 1.0, v168
	v_add_f32_e32 v169, 1.0, v169
	v_add_f32_e32 v170, 1.0, v170
	v_add_f32_e32 v171, 1.0, v171
	v_add_f32_e32 v172, 1.0, v172
	v_add_f32_e32 v173, 1.0, v173
	v_rcp_f32_e32 v164, v164
	v_rcp_f32_e32 v165, v165
	v_rcp_f32_e32 v168, v168
	v_rcp_f32_e32 v169, v169
	v_rcp_f32_e32 v170, v170
	v_rcp_f32_e32 v171, v171
	v_rcp_f32_e32 v172, v172
	v_rcp_f32_e32 v173, v173
	v_mul_f32_e32 v164, v60, v164
	v_mul_f32_e32 v165, v61, v165
	v_mul_f32_e32 v168, v62, v168
	v_mul_f32_e32 v169, v63, v169
	v_mul_f32_e32 v170, v68, v170
	v_mul_f32_e32 v171, v69, v171
	v_mul_f32_e32 v172, v70, v172
	v_mul_f32_e32 v173, v71, v173
	v_mul_f32_e32 v164, v164, v120
	v_mul_f32_e32 v165, v165, v121
	v_mul_f32_e32 v168, v168, v122
	v_mul_f32_e32 v169, v169, v123
	v_mul_f32_e32 v170, v170, v124
	v_mul_f32_e32 v171, v171, v125
	v_mul_f32_e32 v172, v172, v126
	v_mul_f32_e32 v173, v173, v127
	s_mul_i32 vcc_lo, s78, 0xa0
	s_mov_b32 vcc_hi, 0
	v_lshl_add_u64 v[174:175], v[174:175], 0, vcc
	v_cvt_pk_bf16_f32 v164, v164, v165
	v_cvt_pk_bf16_f32 v165, v168, v169
	v_cvt_pk_bf16_f32 v166, v170, v171
	v_cvt_pk_bf16_f32 v167, v172, v173
	global_store_dwordx4 v[174:175], v[164:167], off
	s_nop 1
	v_mul_f32_e32 v169, 0xbfb8aa3b, v51
	v_mul_f32_e32 v164, 0xbfb8aa3b, v48
	v_mul_f32_e32 v165, 0xbfb8aa3b, v49
	v_mul_f32_e32 v168, 0xbfb8aa3b, v50
	v_mul_f32_e32 v170, 0xbfb8aa3b, v52
	v_mul_f32_e32 v171, 0xbfb8aa3b, v53
	v_mul_f32_e32 v172, 0xbfb8aa3b, v54
	v_mul_f32_e32 v173, 0xbfb8aa3b, v55
	v_exp_f32_e32 v164, v164
	v_exp_f32_e32 v165, v165
	v_exp_f32_e32 v168, v168
	v_exp_f32_e32 v169, v169
	v_exp_f32_e32 v170, v170
	v_exp_f32_e32 v171, v171
	v_exp_f32_e32 v172, v172
	v_exp_f32_e32 v173, v173
	v_add_f32_e32 v164, 1.0, v164
	v_add_f32_e32 v165, 1.0, v165
	v_add_f32_e32 v168, 1.0, v168
	v_add_f32_e32 v169, 1.0, v169
; DI unsigned pk2(float lo, float hi) { f32x2 v = {lo, hi}; bf16v2 b = __builtin_convertvector(v, bf16v2); return __builtin_bit_cast(unsigned, b); }
; DI float silu_f(float x) { return x * __builtin_amdgcn_rcpf(1.f + __expf(-x)); }
;     DI void operator()(const f32x4 (&acc)[2][2][4][2], const Unit& u, int wr, int wc, int fr, int fq) const {
;     ...
;             for (int m = 0; m < 4; ++m) { bf16_t* rowp = O + (size_t)(row0 + ai * HALF + m * 16) * ldc + col0;
;                 float r[8];
; #pragma unroll
;                 for (int n = 0; n < 2; ++n)
; #pragma unroll
;                     for (int e = 0; e < 4; ++e) { const float g = acc[ai][0][m][n][e], up = acc[ai][1][m][n][e]; r[n * 4 + e] = silu_f(g) * up; }
;                 u32x4 o; o.x = pk2(r[0], r[1]); o.y = pk2(r[2], r[3]); o.z = pk2(r[4], r[5]); o.w = pk2(r[6], r[7]);
;                 *(u32x4*)rowp = o; }
	v_add_f32_e32 v170, 1.0, v170
	v_add_f32_e32 v171, 1.0, v171
	v_add_f32_e32 v172, 1.0, v172
	v_add_f32_e32 v173, 1.0, v173
	v_rcp_f32_e32 v164, v164
	v_rcp_f32_e32 v165, v165
	v_rcp_f32_e32 v168, v168
	v_rcp_f32_e32 v169, v169
	v_rcp_f32_e32 v170, v170
	v_rcp_f32_e32 v171, v171
	v_rcp_f32_e32 v172, v172
	v_rcp_f32_e32 v173, v173
	v_mul_f32_e32 v164, v48, v164
	v_mul_f32_e32 v165, v49, v165
	v_mul_f32_e32 v168, v50, v168
	v_mul_f32_e32 v169, v51, v169
	v_mul_f32_e32 v170, v52, v170
	v_mul_f32_e32 v171, v53, v171
	v_mul_f32_e32 v172, v54, v172
	v_mul_f32_e32 v173, v55, v173
	v_mul_f32_e32 v164, v164, v112
	v_mul_f32_e32 v165, v165, v113
	v_mul_f32_e32 v168, v168, v114
	v_mul_f32_e32 v169, v169, v115
	v_mul_f32_e32 v170, v170, v116
	v_mul_f32_e32 v171, v171, v117
	v_mul_f32_e32 v172, v172, v118
	v_mul_f32_e32 v173, v173, v119
	v_lshl_add_u64 v[174:175], v[174:175], 0, s[100:101]
	v_cvt_pk_bf16_f32 v164, v164, v165
	v_cvt_pk_bf16_f32 v165, v168, v169
	v_cvt_pk_bf16_f32 v166, v170, v171
	v_cvt_pk_bf16_f32 v167, v172, v173
	global_store_dwordx4 v[174:175], v[164:167], off
	s_nop 1
	v_mul_f32_e32 v170, 0xbfb8aa3b, v44
	v_mul_f32_e32 v164, 0xbfb8aa3b, v40
	v_mul_f32_e32 v165, 0xbfb8aa3b, v41
	v_mul_f32_e32 v168, 0xbfb8aa3b, v42
	v_mul_f32_e32 v169, 0xbfb8aa3b, v43
	v_mul_f32_e32 v171, 0xbfb8aa3b, v45
	v_mul_f32_e32 v172, 0xbfb8aa3b, v46
	v_mul_f32_e32 v173, 0xbfb8aa3b, v47
	v_exp_f32_e32 v164, v164
	v_exp_f32_e32 v165, v165
	v_exp_f32_e32 v168, v168
	v_exp_f32_e32 v169, v169
	v_exp_f32_e32 v170, v170
	v_exp_f32_e32 v171, v171
	v_exp_f32_e32 v172, v172
	v_exp_f32_e32 v173, v173
	v_add_f32_e32 v164, 1.0, v164
	v_add_f32_e32 v165, 1.0, v165
	v_add_f32_e32 v168, 1.0, v168
	v_add_f32_e32 v169, 1.0, v169
	v_add_f32_e32 v170, 1.0, v170
	v_add_f32_e32 v171, 1.0, v171
	v_add_f32_e32 v172, 1.0, v172
	v_add_f32_e32 v173, 1.0, v173
	v_rcp_f32_e32 v164, v164
	v_rcp_f32_e32 v165, v165
	v_rcp_f32_e32 v168, v168
	v_rcp_f32_e32 v169, v169
	v_rcp_f32_e32 v170, v170
	v_rcp_f32_e32 v171, v171
	v_rcp_f32_e32 v172, v172
	v_rcp_f32_e32 v173, v173
	v_mul_f32_e32 v164, v40, v164
	v_mul_f32_e32 v165, v41, v165
	v_mul_f32_e32 v168, v42, v168
	v_mul_f32_e32 v169, v43, v169
	v_mul_f32_e32 v170, v44, v170
	v_mul_f32_e32 v171, v45, v171
	v_mul_f32_e32 v172, v46, v172
	v_mul_f32_e32 v173, v47, v173
	v_mul_f32_e32 v164, v164, v104
	v_mul_f32_e32 v165, v165, v105
	v_mul_f32_e32 v168, v168, v106
	v_mul_f32_e32 v169, v169, v107
	v_mul_f32_e32 v170, v170, v108
	v_mul_f32_e32 v171, v171, v109
	v_mul_f32_e32 v172, v172, v110
	v_mul_f32_e32 v173, v173, v111
	v_lshl_add_u64 v[174:175], v[174:175], 0, s[100:101]
	v_cvt_pk_bf16_f32 v164, v164, v165
	v_cvt_pk_bf16_f32 v165, v168, v169
	v_cvt_pk_bf16_f32 v166, v170, v171
	v_cvt_pk_bf16_f32 v167, v172, v173
	global_store_dwordx4 v[174:175], v[164:167], off
	s_nop 1
	v_mul_f32_e32 v170, 0xbfb8aa3b, v36
	v_mul_f32_e32 v164, 0xbfb8aa3b, v32
	v_mul_f32_e32 v165, 0xbfb8aa3b, v33
	v_mul_f32_e32 v168, 0xbfb8aa3b, v34
	v_mul_f32_e32 v169, 0xbfb8aa3b, v35
	v_mul_f32_e32 v171, 0xbfb8aa3b, v37
	v_mul_f32_e32 v172, 0xbfb8aa3b, v38
	v_mul_f32_e32 v173, 0xbfb8aa3b, v39
	v_exp_f32_e32 v164, v164
	v_exp_f32_e32 v165, v165
	v_exp_f32_e32 v168, v168
	v_exp_f32_e32 v169, v169
	v_exp_f32_e32 v170, v170
	v_exp_f32_e32 v171, v171
	v_exp_f32_e32 v172, v172
	v_exp_f32_e32 v173, v173
	v_add_f32_e32 v164, 1.0, v164
	v_add_f32_e32 v165, 1.0, v165
	v_add_f32_e32 v168, 1.0, v168
	v_add_f32_e32 v169, 1.0, v169
	v_add_f32_e32 v170, 1.0, v170
	v_add_f32_e32 v171, 1.0, v171
	v_add_f32_e32 v172, 1.0, v172
	v_add_f32_e32 v173, 1.0, v173
	v_rcp_f32_e32 v164, v164
	v_rcp_f32_e32 v165, v165
	v_rcp_f32_e32 v168, v168
	v_rcp_f32_e32 v169, v169
	v_rcp_f32_e32 v170, v170
	v_rcp_f32_e32 v171, v171
	v_rcp_f32_e32 v172, v172
	v_rcp_f32_e32 v173, v173
	v_mul_f32_e32 v164, v32, v164
	v_mul_f32_e32 v165, v33, v165
	v_mul_f32_e32 v168, v34, v168
	v_mul_f32_e32 v169, v35, v169
	v_mul_f32_e32 v170, v36, v170
	v_mul_f32_e32 v171, v37, v171
	v_mul_f32_e32 v172, v38, v172
	v_mul_f32_e32 v173, v39, v173
	v_mul_f32_e32 v164, v164, v92
	v_mul_f32_e32 v165, v165, v93
	v_mul_f32_e32 v168, v168, v94
	v_mul_f32_e32 v169, v169, v95
	v_mul_f32_e32 v170, v170, v100
	v_mul_f32_e32 v171, v171, v101
	v_mul_f32_e32 v172, v172, v102
	v_mul_f32_e32 v173, v173, v103
	v_lshl_add_u64 v[174:175], v[174:175], 0, s[100:101]
	v_cvt_pk_bf16_f32 v164, v164, v165
	v_cvt_pk_bf16_f32 v165, v168, v169
	v_cvt_pk_bf16_f32 v166, v170, v171
	v_cvt_pk_bf16_f32 v167, v172, v173
	global_store_dwordx4 v[174:175], v[164:167], off
	s_nop 1
	s_cbranch_execnz .LBB0_748
	s_branch .LBB0_747
